# out-projection 0 epilogue: first 12 residual (x) loads issued at the top of the epilogue (5 destinations and one address temp renamed to free VGPRs), ahead of the two modulation-vector round trips
# speedup vs baseline: 1.0305x; 1.0032x over previous
.LBB0_822:
	v_mov_b32_e32 v233, v244
	s_mov_b64 s[26:27], s[0:1]
	s_load_dwordx2 s[68:69], s[26:27], 0xa8
	s_load_dwordx2 s[72:73], s[26:27], 0x0
	s_nop 0
	s_load_dwordx2 s[26:27], s[26:27], 0x20
	s_ashr_i32 s92, s4, 3
	s_ashr_i32 s93, s92, 31
	s_lshl_b64 s[70:71], s[92:93], 22
	s_waitcnt lgkmcnt(0)
	s_add_u32 s70, s68, s70
	s_addc_u32 s71, s69, s71
	s_add_u32 s5, s68, 0x100000
	s_mulk_i32 s92, 0xc00
	s_addc_u32 s61, s69, 0
	s_lshl_b32 s77, s90, 8
	s_ashr_i32 s93, s92, 31
	s_or_b32 s77, s77, s80
	v_ashrrev_i32_e32 v104, 1, v233
	s_lshl_b64 s[94:95], s[92:93], 2
	v_and_b32_e32 v104, -8, v104
	s_add_u32 s94, s5, s94
	v_add_u32_e32 v144, s77, v104
	s_addc_u32 s95, s61, s95
	s_addk_i32 s92, 0x6c00
	s_ashr_i32 s93, s92, 31
	v_ashrrev_i32_e32 v145, 31, v144
	s_lshl_b64 s[92:93], s[92:93], 2
	v_lshlrev_b64 v[146:147], 2, v[144:145]
	s_add_u32 s92, s5, s92
	v_lshl_add_u64 v[104:105], s[94:95], 0, v[146:147]
	s_movk_i32 s5, 0x2000
	v_lshl_add_u64 v[156:157], v[104:105], 0, s[12:13]
	v_add_co_u32_e32 v104, vcc, s5, v104
	v_lshl_add_u64 v[128:129], s[26:27], 0, v[146:147]
	s_nop 0
	v_addc_co_u32_e32 v105, vcc, 0, v105, vcc
	s_addc_u32 s93, s61, s93
	s_ashr_i32 s5, s4, 31
	s_lshl_b64 s[4:5], s[4:5], 8
	s_add_u32 s4, s4, s79
	s_addc_u32 s5, s5, 0
	v_and_or_b32 v224, v233, 15, s4
	v_mov_b32_e32 v225, s5
	s_mov_b32 s4, 0x10000
	v_lshl_add_u64 v[144:145], v[144:145], 1, s[70:71]
	v_lshl_add_u64 v[220:221], v[144:145], 0, s[34:35]
	s_lshl_b32 s26, s90, 2
	s_ashr_i32 s27, s26, 31
	s_lshl_b64 s[26:27], s[26:27], 2
	s_add_u32 s26, s68, s26
	s_addc_u32 s27, s69, s27
	s_add_u32 s26, s26, s87
	s_addc_u32 s27, s27, 0
	s_add_u32 s68, s26, 0x1700000
	s_addc_u32 s69, s27, 0
	v_lshlrev_b64 v[148:149], 12, v[224:225]
	v_lshl_add_u64 v[148:149], s[72:73], 0, v[148:149]
	v_lshl_add_u64 v[222:223], v[148:149], 0, v[146:147]
	v_lshl_add_u64 v[240:241], v[222:223], 0, s[16:17]
	global_load_dwordx4 v[184:187], v[222:223], off offset:16 nt
	global_load_dwordx4 v[188:191], v[222:223], off nt
	global_load_dwordx4 v[176:179], v[222:223], off offset:528 nt
	global_load_dwordx4 v[180:183], v[222:223], off offset:512 nt
	v_add_co_u32_e32 v148, vcc, s4, v222
	v_lshl_add_u64 v[144:145], v[222:223], 0, s[36:37]
	s_nop 0
	v_addc_co_u32_e32 v149, vcc, 0, v223, vcc
	global_load_dwordx4 v[172:175], v[148:149], off nt
	global_load_dwordx4 v[168:171], v[240:241], off offset:16 nt
	v_lshl_add_u64 v[240:241], v[222:223], 0, s[18:19]
	global_load_dwordx4 v[164:167], v[148:149], off offset:512 nt
	global_load_dwordx4 v[192:195], v[240:241], off offset:16 nt
	v_add_co_u32_e32 v240, vcc, s88, v222
	s_nop 1
	v_addc_co_u32_e32 v241, vcc, 0, v223, vcc
	global_load_dwordx4 v[196:199], v[240:241], off nt
	global_load_dwordx4 v[200:203], v[144:145], off offset:16 nt
	v_lshl_add_u64 v[144:145], v[222:223], 0, s[38:39]
	global_load_dwordx4 v[228:231], v[240:241], off offset:512 nt
	s_nop 0
	global_load_dwordx4 v[236:239], v[144:145], off offset:16 nt
	v_lshl_add_u64 v[158:159], v[128:129], 0, s[14:15]
	v_add_co_u32_e32 v128, vcc, s85, v128
	v_lshl_add_u64 v[148:149], s[92:93], 0, v[146:147]
	s_nop 0
	v_addc_co_u32_e32 v129, vcc, 0, v129, vcc
	v_lshl_add_u64 v[160:161], v[148:149], 0, s[14:15]
	v_add_co_u32_e32 v148, vcc, s85, v148
	global_load_dwordx4 v[108:111], v[104:105], off
	s_nop 0
	global_load_dwordx4 v[104:107], v[156:157], off offset:16
	v_addc_co_u32_e32 v149, vcc, 0, v149, vcc
	global_load_dwordx4 v[128:131], v[128:129], off
	s_nop 0
	global_load_dwordx4 v[132:135], v[158:159], off offset:16
	s_nop 0
	global_load_dwordx4 v[148:151], v[148:149], off
	s_nop 0
	global_load_dwordx4 v[152:155], v[160:161], off offset:16
	s_waitcnt vmcnt(0)
	v_pk_add_f32 v[148:149], v[148:149], 1.0 op_sel_hi:[1,0]
	s_nop 0
	v_pk_mul_f32 v[128:129], v[128:129], v[148:149]
	v_pk_add_f32 v[150:151], v[150:151], 1.0 op_sel_hi:[1,0]
	v_cmp_nlt_f32_e64 vcc, |v128|, s86
	v_pk_mul_f32 v[130:131], v[130:131], v[150:151]
	s_nop 0
	v_cndmask_b32_e32 v204, v232, v128, vcc
	v_cmp_nlt_f32_e64 vcc, |v129|, s86
	s_nop 1
	v_cndmask_b32_e32 v205, v232, v129, vcc
	v_cmp_nlt_f32_e64 vcc, |v130|, s86
	v_pk_add_f32 v[128:129], v[154:155], 1.0 op_sel_hi:[1,0]
	s_nop 0
	v_cndmask_b32_e32 v206, v232, v130, vcc
	v_cmp_nlt_f32_e64 vcc, |v131|, s86
	v_pk_mul_f32 v[128:129], v[134:135], v[128:129]
	s_nop 0
	v_cndmask_b32_e32 v207, v232, v131, vcc
	v_pk_add_f32 v[130:131], v[152:153], 1.0 op_sel_hi:[1,0]
	s_nop 0
	v_pk_mul_f32 v[130:131], v[132:133], v[130:131]
	s_nop 0
	v_cmp_nlt_f32_e64 vcc, |v130|, s86
	s_nop 1
	v_cndmask_b32_e32 v208, v232, v130, vcc
	v_cmp_nlt_f32_e64 vcc, |v131|, s86
	s_nop 1
	v_cndmask_b32_e32 v209, v232, v131, vcc
	v_cmp_nlt_f32_e64 vcc, |v128|, s86
	s_nop 1
	v_cndmask_b32_e32 v210, v232, v128, vcc
	v_cmp_nlt_f32_e64 vcc, |v129|, s86
	s_nop 1
	v_cndmask_b32_e32 v211, v232, v129, vcc
	global_load_dwordx4 v[128:131], v[156:157], off offset:528
	global_load_dwordx4 v[132:135], v[156:157], off offset:512
	global_load_dwordx4 v[148:151], v[158:159], off offset:528
	global_load_dwordx4 v[152:155], v[158:159], off offset:512
	s_nop 0
	global_load_dwordx4 v[156:159], v[160:161], off offset:528
	s_nop 0
	global_load_dwordx4 v[160:163], v[160:161], off offset:512
	s_waitcnt vmcnt(0)
	v_pk_add_f32 v[160:161], v[160:161], 1.0 op_sel_hi:[1,0]
	s_nop 0
	v_pk_mul_f32 v[152:153], v[152:153], v[160:161]
	v_pk_add_f32 v[162:163], v[162:163], 1.0 op_sel_hi:[1,0]
	v_cmp_nlt_f32_e64 vcc, |v152|, s86
	v_pk_mul_f32 v[154:155], v[154:155], v[162:163]
	s_nop 0
	v_cndmask_b32_e32 v212, v232, v152, vcc
	v_cmp_nlt_f32_e64 vcc, |v153|, s86
	s_nop 1
	v_cndmask_b32_e32 v213, v232, v153, vcc
	v_cmp_nlt_f32_e64 vcc, |v154|, s86
	v_pk_add_f32 v[152:153], v[158:159], 1.0 op_sel_hi:[1,0]
	s_nop 0
	v_cndmask_b32_e32 v218, v232, v154, vcc
	v_cmp_nlt_f32_e64 vcc, |v155|, s86
	v_pk_mul_f32 v[150:151], v[150:151], v[152:153]
	s_nop 0
	v_cndmask_b32_e32 v219, v232, v155, vcc
	v_pk_add_f32 v[154:155], v[156:157], 1.0 op_sel_hi:[1,0]
	s_nop 0
	v_pk_mul_f32 v[148:149], v[148:149], v[154:155]
	s_nop 0
	v_cmp_nlt_f32_e64 vcc, |v148|, s86
	s_nop 1
	v_cndmask_b32_e32 v214, v232, v148, vcc
	v_cmp_nlt_f32_e64 vcc, |v149|, s86
	s_nop 1
	v_cndmask_b32_e32 v215, v232, v149, vcc
	v_cmp_nlt_f32_e64 vcc, |v150|, s86
	s_nop 1
	v_cndmask_b32_e32 v216, v232, v150, vcc
	v_cmp_nlt_f32_e64 vcc, |v151|, s86
	s_nop 1
	v_cndmask_b32_e32 v217, v232, v151, vcc
	v_cmp_gt_u32_e64 s[4:5], 16, v233
	s_waitcnt vmcnt(10)
	v_pk_fma_f32 v[142:143], v[142:143], v[110:111], v[190:191]
	v_pk_fma_f32 v[140:141], v[140:141], v[108:109], v[188:189]
	v_pk_fma_f32 v[136:137], v[136:137], v[104:105], v[184:185]
	v_mul_f32_e32 v184, v141, v141
	v_mul_f32_e32 v185, v143, v143
	v_fmac_f32_e32 v184, v140, v140
	v_fmac_f32_e32 v185, v142, v142
	v_add_f32_e32 v184, v184, v185
	v_mul_f32_e32 v185, v137, v137
	v_pk_fma_f32 v[138:139], v[138:139], v[106:107], v[186:187]
	v_fmac_f32_e32 v185, v136, v136
	v_add_f32_e32 v184, v184, v185
	v_mul_f32_e32 v185, v139, v139
	v_fmac_f32_e32 v185, v138, v138
	v_lshlrev_b64 v[234:235], 11, v[224:225]
	v_add_f32_e32 v186, v185, v184
	v_pk_mul_f32 v[142:143], v[206:207], v[142:143]
	v_pk_mul_f32 v[140:141], v[204:205], v[140:141]
	v_pk_mul_f32 v[184:185], v[210:211], v[138:139]
	v_pk_mul_f32 v[138:139], v[208:209], v[136:137]
	v_lshl_add_u64 v[234:235], v[220:221], 0, v[234:235]
	v_cvt_pk_bf16_f32 v136, v140, v141
	v_cvt_pk_bf16_f32 v137, v142, v143
	v_cvt_pk_bf16_f32 v138, v138, v139
	v_cvt_pk_bf16_f32 v139, v184, v185
	s_waitcnt vmcnt(8)
	v_pk_fma_f32 v[126:127], v[126:127], v[134:135], v[182:183]
	v_pk_fma_f32 v[124:125], v[124:125], v[132:133], v[180:181]
	global_store_dwordx4 v[234:235], v[136:139], off
	v_pk_fma_f32 v[120:121], v[120:121], v[128:129], v[176:177]
	v_pk_fma_f32 v[122:123], v[122:123], v[130:131], v[178:179]
	v_mul_f32_e32 v136, v125, v125
	v_mul_f32_e32 v137, v127, v127
	v_fmac_f32_e32 v136, v124, v124
	v_fmac_f32_e32 v137, v126, v126
	v_add_f32_e32 v136, v136, v137
	v_mul_f32_e32 v137, v121, v121
	v_fmac_f32_e32 v137, v120, v120
	v_add_f32_e32 v136, v136, v137
	v_mul_f32_e32 v137, v123, v123
	v_fmac_f32_e32 v137, v122, v122
	v_add_f32_e32 v136, v137, v136
	v_add_f32_e32 v140, v186, v136
	ds_bpermute_b32 v141, v226, v140
	v_pk_mul_f32 v[138:139], v[120:121], v[214:215]
	v_pk_mul_f32 v[126:127], v[126:127], v[218:219]
	v_pk_mul_f32 v[124:125], v[124:125], v[212:213]
	v_pk_mul_f32 v[136:137], v[122:123], v[216:217]
	s_waitcnt lgkmcnt(0)
	v_add_f32_e32 v120, v140, v141
	ds_bpermute_b32 v121, v227, v120
	v_cvt_pk_bf16_f32 v122, v124, v125
	v_cvt_pk_bf16_f32 v123, v126, v127
	v_cvt_pk_bf16_f32 v124, v138, v139
	v_cvt_pk_bf16_f32 v125, v136, v137
	global_store_dwordx4 v[234:235], v[122:125], off offset:256
	s_and_saveexec_b64 s[70:71], s[4:5]
	s_cbranch_execz .LBB0_824
	v_lshlrev_b64 v[122:123], 6, v[224:225]
	v_lshl_add_u64 v[122:123], s[68:69], 0, v[122:123]
	s_waitcnt lgkmcnt(0)
	v_add_f32_e32 v120, v120, v121
	global_store_dword v[122:123], v120, off
.LBB0_824:
	s_or_b64 exec, exec, s[70:71]
	v_add_co_u32_e32 v122, vcc, 0x30000, v222
	s_waitcnt lgkmcnt(0)
	v_lshl_add_u64 v[120:121], v[222:223], 0, s[40:41]
	v_addc_co_u32_e32 v123, vcc, 0, v223, vcc
	global_load_dwordx4 v[140:143], v[122:123], off nt
	global_load_dwordx4 v[136:139], v[120:121], off offset:16 nt
	v_lshl_add_u64 v[120:121], v[222:223], 0, s[42:43]
	global_load_dwordx4 v[124:127], v[122:123], off offset:512 nt
	s_nop 0
	global_load_dwordx4 v[120:123], v[120:121], off offset:16 nt
	s_waitcnt vmcnt(13)
	v_pk_fma_f32 v[118:119], v[118:119], v[110:111], v[174:175]
	v_pk_fma_f32 v[116:117], v[116:117], v[108:109], v[172:173]
	s_waitcnt vmcnt(12)
	v_pk_fma_f32 v[112:113], v[112:113], v[104:105], v[168:169]
	v_mul_f32_e32 v168, v117, v117
	v_mul_f32_e32 v169, v119, v119
	v_fmac_f32_e32 v168, v116, v116
	v_fmac_f32_e32 v169, v118, v118
	v_add_f32_e32 v168, v168, v169
	v_mul_f32_e32 v169, v113, v113
	v_pk_fma_f32 v[114:115], v[114:115], v[106:107], v[170:171]
	v_fmac_f32_e32 v169, v112, v112
	v_add_f32_e32 v168, v168, v169
	v_mul_f32_e32 v169, v115, v115
	v_or_b32_e32 v176, 16, v224
	v_mov_b32_e32 v177, v225
	v_fmac_f32_e32 v169, v114, v114
	v_lshlrev_b64 v[178:179], 11, v[176:177]
	v_add_f32_e32 v170, v169, v168
	v_pk_mul_f32 v[118:119], v[206:207], v[118:119]
	v_pk_mul_f32 v[116:117], v[204:205], v[116:117]
	v_pk_mul_f32 v[168:169], v[210:211], v[114:115]
	v_pk_mul_f32 v[114:115], v[208:209], v[112:113]
	v_lshl_add_u64 v[178:179], v[220:221], 0, v[178:179]
	v_cvt_pk_bf16_f32 v112, v116, v117
	v_cvt_pk_bf16_f32 v113, v118, v119
	v_cvt_pk_bf16_f32 v114, v114, v115
	v_cvt_pk_bf16_f32 v115, v168, v169
	s_waitcnt vmcnt(11)
	v_pk_fma_f32 v[102:103], v[102:103], v[134:135], v[166:167]
	v_pk_fma_f32 v[100:101], v[100:101], v[132:133], v[164:165]
	global_store_dwordx4 v[178:179], v[112:115], off
	s_waitcnt vmcnt(11)
	v_pk_fma_f32 v[96:97], v[96:97], v[128:129], v[192:193]
	v_pk_fma_f32 v[98:99], v[98:99], v[130:131], v[194:195]
	v_mul_f32_e32 v112, v101, v101
	v_mul_f32_e32 v113, v103, v103
	v_fmac_f32_e32 v112, v100, v100
	v_fmac_f32_e32 v113, v102, v102
	v_add_f32_e32 v112, v112, v113
	v_mul_f32_e32 v113, v97, v97
	v_fmac_f32_e32 v113, v96, v96
	v_add_f32_e32 v112, v112, v113
	v_mul_f32_e32 v113, v99, v99
	v_fmac_f32_e32 v113, v98, v98
	v_add_f32_e32 v112, v113, v112
	v_add_f32_e32 v116, v170, v112
	ds_bpermute_b32 v117, v226, v116
	v_pk_mul_f32 v[114:115], v[214:215], v[96:97]
	v_pk_mul_f32 v[102:103], v[218:219], v[102:103]
	v_pk_mul_f32 v[100:101], v[212:213], v[100:101]
	v_pk_mul_f32 v[112:113], v[216:217], v[98:99]
	s_waitcnt lgkmcnt(0)
	v_add_f32_e32 v96, v116, v117
	ds_bpermute_b32 v97, v227, v96
	v_cvt_pk_bf16_f32 v98, v100, v101
	v_cvt_pk_bf16_f32 v99, v102, v103
	v_cvt_pk_bf16_f32 v100, v114, v115
	v_cvt_pk_bf16_f32 v101, v112, v113
	global_store_dwordx4 v[178:179], v[98:101], off offset:256
	s_and_saveexec_b64 s[70:71], s[4:5]
	s_cbranch_execz .LBB0_826
	v_lshlrev_b64 v[98:99], 6, v[176:177]
	v_lshl_add_u64 v[98:99], s[68:69], 0, v[98:99]
	s_waitcnt lgkmcnt(0)
	v_add_f32_e32 v96, v96, v97
	global_store_dword v[98:99], v96, off
.LBB0_826:
	s_or_b64 exec, exec, s[70:71]
	v_add_co_u32_e32 v98, vcc, 0x80000, v222
	s_waitcnt lgkmcnt(0)
	v_lshl_add_u64 v[96:97], v[222:223], 0, s[44:45]
	v_addc_co_u32_e32 v99, vcc, 0, v223, vcc
	global_load_dwordx4 v[116:119], v[98:99], off nt
	global_load_dwordx4 v[112:115], v[96:97], off offset:16 nt
	v_lshl_add_u64 v[96:97], v[222:223], 0, s[46:47]
	global_load_dwordx4 v[100:103], v[98:99], off offset:512 nt
	s_nop 0
	global_load_dwordx4 v[96:99], v[96:97], off offset:16 nt
	s_waitcnt vmcnt(15)
	v_pk_fma_f32 v[94:95], v[94:95], v[110:111], v[198:199]
	v_pk_fma_f32 v[92:93], v[92:93], v[108:109], v[196:197]
	s_waitcnt vmcnt(14)
	v_pk_fma_f32 v[88:89], v[88:89], v[104:105], v[200:201]
	v_mul_f32_e32 v152, v93, v93
	v_mul_f32_e32 v153, v95, v95
	v_fmac_f32_e32 v152, v92, v92
	v_fmac_f32_e32 v153, v94, v94
	v_add_f32_e32 v152, v152, v153
	v_mul_f32_e32 v153, v89, v89
	v_pk_fma_f32 v[90:91], v[90:91], v[106:107], v[202:203]
	v_fmac_f32_e32 v153, v88, v88
	v_add_f32_e32 v152, v152, v153
	v_mul_f32_e32 v153, v91, v91
	v_or_b32_e32 v160, 32, v224
	v_mov_b32_e32 v161, v225
	v_fmac_f32_e32 v153, v90, v90
	v_lshlrev_b64 v[162:163], 11, v[160:161]
	v_add_f32_e32 v154, v153, v152
	v_pk_mul_f32 v[94:95], v[206:207], v[94:95]
	v_pk_mul_f32 v[92:93], v[204:205], v[92:93]
	v_pk_mul_f32 v[152:153], v[210:211], v[90:91]
	v_pk_mul_f32 v[90:91], v[208:209], v[88:89]
	v_lshl_add_u64 v[162:163], v[220:221], 0, v[162:163]
	v_cvt_pk_bf16_f32 v88, v92, v93
	v_cvt_pk_bf16_f32 v89, v94, v95
	v_cvt_pk_bf16_f32 v90, v90, v91
	v_cvt_pk_bf16_f32 v91, v152, v153
	s_waitcnt vmcnt(13)
	v_pk_fma_f32 v[86:87], v[86:87], v[134:135], v[230:231]
	v_pk_fma_f32 v[84:85], v[84:85], v[132:133], v[228:229]
	global_store_dwordx4 v[162:163], v[88:91], off
	s_waitcnt vmcnt(13)
	v_pk_fma_f32 v[80:81], v[80:81], v[128:129], v[236:237]
	v_pk_fma_f32 v[82:83], v[82:83], v[130:131], v[238:239]
	v_mul_f32_e32 v88, v85, v85
	v_mul_f32_e32 v89, v87, v87
	v_fmac_f32_e32 v88, v84, v84
	v_fmac_f32_e32 v89, v86, v86
	v_add_f32_e32 v88, v88, v89
	v_mul_f32_e32 v89, v81, v81
	v_fmac_f32_e32 v89, v80, v80
	v_add_f32_e32 v88, v88, v89
	v_mul_f32_e32 v89, v83, v83
	v_fmac_f32_e32 v89, v82, v82
	v_add_f32_e32 v88, v89, v88
	v_add_f32_e32 v92, v154, v88
	ds_bpermute_b32 v93, v226, v92
	v_pk_mul_f32 v[90:91], v[214:215], v[80:81]
	v_pk_mul_f32 v[86:87], v[218:219], v[86:87]
	v_pk_mul_f32 v[84:85], v[212:213], v[84:85]
	v_pk_mul_f32 v[88:89], v[216:217], v[82:83]
	s_waitcnt lgkmcnt(0)
	v_add_f32_e32 v80, v92, v93
	ds_bpermute_b32 v81, v227, v80
	v_cvt_pk_bf16_f32 v82, v84, v85
	v_cvt_pk_bf16_f32 v83, v86, v87
	v_cvt_pk_bf16_f32 v84, v90, v91
	v_cvt_pk_bf16_f32 v85, v88, v89
	global_store_dwordx4 v[162:163], v[82:85], off offset:256
	s_and_saveexec_b64 s[70:71], s[4:5]
	s_cbranch_execz .LBB0_828
	v_lshlrev_b64 v[82:83], 6, v[160:161]
	v_lshl_add_u64 v[82:83], s[68:69], 0, v[82:83]
	s_waitcnt lgkmcnt(0)
	v_add_f32_e32 v80, v80, v81
	global_store_dword v[82:83], v80, off
